# v056 plus: two hazard nops in the softmax-finish section replaced by reordering independent cvt instructions
# baseline (speedup 1.0000x reference)
; __device__ __forceinline__ void finishSM(f32x16& p0, f32x16& p1, float alpha, float& l_reg, bf16x8& pa0, bf16x8& pa1, bf16x8& pa2, bf16x8& pa3) {
; #pragma unroll
;   for (int r = 0; r < 16; ++r) p1[r] = __builtin_amdgcn_exp2f(p1[r]);
;   float ps = 0;
; #pragma unroll
;   for (int r = 0; r < 16; ++r) ps += p0[r];
; #pragma unroll
;   for (int r = 0; r < 16; ++r) ps += p1[r];
;   { auto rr = __builtin_amdgcn_permlane32_swap(__float_as_uint(ps), __float_as_uint(ps), false, false);
;     ps = __uint_as_float(rr[0]) + __uint_as_float(rr[1]); }
;   l_reg = l_reg * alpha + ps;
;     ...
;   PK4(p0, 0, pa0); PK4(p0, 8, pa1); PK4(p1, 0, pa2); PK4(p1, 8, pa3);
;     ...
; }
; template <int NQ> __device__ __forceinline__ void qkt(f32x16& p0, f32x16& p1, const char* Ks, const bf16x8* qr, int r32, int hi, int kcolB) {
;   p0 = f32x16{}; p1 = f32x16{};
; #pragma unroll
;   for (int d0 = 0; d0 < NQ; ++d0) { const int cb = kcolB + (d0 * 16 + hi * 8) * 2;
;     bf16x8 b0 = *reinterpret_cast<const bf16x8*>(Ks + KSWZ(r32, cb));
;     bf16x8 b1 = *reinterpret_cast<const bf16x8*>(Ks + KSWZ(32 + r32, cb));
;     p0 = __builtin_amdgcn_mfma_f32_32x32x16_bf16(b0, qr[d0], p0, 0, 0, 0);
;     p1 = __builtin_amdgcn_mfma_f32_32x32x16_bf16(b1, qr[d0], p1, 0, 0, 0); }
; }
; __device__ __forceinline__ void qkt0(f32x16& p0, f32x16& p1, const char* Ks, const char* Qs, int r32, int hi, int kcolB, const f32x16& init) {
; #pragma unroll
;   for (int d0 = 0; d0 < 4; ++d0) { const int cb = kcolB + (d0 * 16 + hi * 8) * 2;
;     bf16x8 b0 = *reinterpret_cast<const bf16x8*>(Ks + KSWZ(r32, cb));
;     bf16x8 b1 = *reinterpret_cast<const bf16x8*>(Ks + KSWZ(32 + r32, cb));
;     bf16x8 qf = *reinterpret_cast<const bf16x8*>(Qs + r32 * 128 + (((2 * d0 + hi) ^ (r32 & 7)) << 4));
;     if (d0 == 0) { p0 = __builtin_amdgcn_mfma_f32_32x32x16_bf16(b0, qf, init, 0, 0, 0); p1 = __builtin_amdgcn_mfma_f32_32x32x16_bf16(b1, qf, init, 0, 0, 0); }
;     else { p0 = __builtin_amdgcn_mfma_f32_32x32x16_bf16(b0, qf, p0, 0, 0, 0); p1 = __builtin_amdgcn_mfma_f32_32x32x16_bf16(b1, qf, p1, 0, 0, 0); } }
; }
.LBB0_215:
	v_add_u32_e32 v112, s59, v193
	v_add_u32_e32 v116, s59, v194
	ds_read_b128 v[112:115], v112 offset:16384
	ds_read_b128 v[202:205], v181
	ds_read_b128 v[206:209], v180
	ds_read_b128 v[210:213], v116 offset:16384
	v_exp_f32_e32 v234, v96
	v_add_f32_e32 v96, 0, v161
	s_waitcnt lgkmcnt(2)
	v_mfma_f32_32x32x16_bf16 v[128:143], v[112:115], v[202:205], v[80:95]
	v_add_u32_e32 v112, s59, v197
	v_add_u32_e32 v113, s59, v195
	v_add_f32_e32 v96, v163, v96
	ds_read_b128 v[214:217], v112 offset:16384
	ds_read_b128 v[218:221], v113 offset:16384
	v_add_f32_e32 v96, v159, v96
	v_add_f32_e32 v96, v162, v96
	v_add_f32_e32 v96, v157, v96
	s_waitcnt lgkmcnt(2)
	v_mfma_f32_32x32x16_bf16 v[112:127], v[210:213], v[202:205], v[80:95]
	v_add_f32_e32 v96, v160, v96
	v_add_f32_e32 v96, v156, v96
	v_add_f32_e32 v96, v158, v96
	v_add_f32_e32 v96, v153, v96
	v_add_f32_e32 v96, v155, v96
	v_add_f32_e32 v96, v151, v96
	v_add_f32_e32 v96, v154, v96
	s_waitcnt lgkmcnt(0)
	v_mfma_f32_32x32x16_bf16 v[128:143], v[218:221], v[206:209], v[128:143]
	v_add_f32_e32 v96, v149, v96
	v_add_u32_e32 v201, s59, v199
	v_add_u32_e32 v210, s59, v196
	v_exp_f32_e32 v235, v97
	v_add_f32_e32 v96, v152, v96
	ds_read_b128 v[202:205], v201 offset:16384
	ds_read_b128 v[210:213], v210 offset:16384
	ds_read_b128 v[222:225], v179
	ds_read_b128 v[226:229], v178
	v_exp_f32_e32 v236, v98
	v_mfma_f32_32x32x16_bf16 v[112:127], v[214:217], v[206:209], v[112:127]
	v_add_f32_e32 v96, v148, v96
	v_exp_f32_e32 v237, v99
	v_add_f32_e32 v96, v150, v96
	v_exp_f32_e32 v238, v100
	v_add_f32_e32 v96, v234, v96
	v_exp_f32_e32 v239, v101
	v_add_f32_e32 v96, v235, v96
	v_exp_f32_e32 v206, v102
	s_waitcnt lgkmcnt(1)
	v_mfma_f32_32x32x16_bf16 v[128:143], v[210:213], v[222:225], v[128:143]
	v_add_f32_e32 v96, v236, v96
	v_exp_f32_e32 v207, v103
	v_add_f32_e32 v96, v237, v96
	v_add_u32_e32 v201, s59, v200
	v_add_u32_e32 v230, s59, v198
	v_exp_f32_e32 v208, v104
	v_add_f32_e32 v96, v238, v96
	v_mfma_f32_32x32x16_bf16 v[112:127], v[202:205], v[222:225], v[112:127]
	ds_read_b128 v[218:221], v201 offset:16384
	ds_read_b128 v[230:233], v230 offset:16384
	v_exp_f32_e32 v209, v105
	v_add_f32_e32 v96, v239, v96
	v_exp_f32_e32 v214, v106
	v_add_f32_e32 v96, v206, v96
	v_exp_f32_e32 v215, v107
	v_add_f32_e32 v96, v207, v96
	v_exp_f32_e32 v216, v108
	v_add_f32_e32 v96, v208, v96
	v_exp_f32_e32 v210, v109
	v_add_f32_e32 v96, v209, v96
	v_exp_f32_e32 v211, v110
	s_waitcnt lgkmcnt(0)
	v_mfma_f32_32x32x16_bf16 v[128:143], v[230:233], v[226:229], v[128:143]
	v_add_f32_e32 v96, v214, v96
	v_exp_f32_e32 v111, v111
	v_add_f32_e32 v96, v215, v96
	v_add_f32_e32 v96, v216, v96
	v_add_f32_e32 v96, v210, v96
	v_add_f32_e32 v96, v211, v96
	v_add_f32_e32 v201, v111, v96
	v_mfma_f32_32x32x16_bf16 v[112:127], v[218:221], v[226:229], v[112:127]
	v_mov_b32_e32 v202, v201
	v_cvt_pk_bf16_f32 v96, v161, v163
	v_cvt_pk_bf16_f32 v97, v159, v162
	v_permlane32_swap_b32_e32 v201, v202
	v_cvt_pk_bf16_f32 v98, v157, v160
	v_cvt_pk_bf16_f32 v99, v156, v158
	v_cvt_pk_bf16_f32 v100, v153, v155
	v_cvt_pk_bf16_f32 v101, v151, v154
	v_cvt_pk_bf16_f32 v102, v149, v152
	v_cvt_pk_bf16_f32 v103, v148, v150
	v_cvt_pk_bf16_f32 v104, v234, v235
	v_cvt_pk_bf16_f32 v105, v236, v237
	v_cvt_pk_bf16_f32 v106, v238, v239
	v_cvt_pk_bf16_f32 v107, v206, v207
	v_cvt_pk_bf16_f32 v108, v208, v209
	v_cvt_pk_bf16_f32 v109, v214, v215
	v_cvt_pk_bf16_f32 v110, v216, v210
	v_cvt_pk_bf16_f32 v111, v211, v111
	v_permlane32_swap_b32_e32 v96, v98
	v_permlane32_swap_b32_e32 v97, v99
	v_permlane32_swap_b32_e32 v100, v102
	v_permlane32_swap_b32_e32 v101, v103
	v_permlane32_swap_b32_e32 v104, v106
	v_permlane32_swap_b32_e32 v105, v107
	v_permlane32_swap_b32_e32 v108, v110
	v_permlane32_swap_b32_e32 v109, v111
	v_add_u32_e32 v203, s36, v175
	ds_read_b64_tr_b16 v[148:149], v203 offset:0
	ds_read_b64_tr_b16 v[150:151], v203 offset:0x800
	ds_read_b64_tr_b16 v[152:153], v203 offset:0x1000
	ds_read_b64_tr_b16 v[154:155], v203 offset:0x1800
	ds_read_b64_tr_b16 v[156:157], v203 offset:0x2000
	ds_read_b64_tr_b16 v[158:159], v203 offset:0x2800
	ds_read_b64_tr_b16 v[160:161], v203 offset:0x3000
	ds_read_b64_tr_b16 v[162:163], v203 offset:0x3800
	s_add_i32 s34, s58, 1
	s_waitcnt lgkmcnt(0)
; __device__ __forceinline__ float rowmax32(const f32x16& p0, const f32x16& p1) {
;   float pmax = p0[0];
; #pragma unroll
;   for (int r = 1; r < 16; ++r) pmax = fmaxf(pmax, p0[r]);
; #pragma unroll
;   for (int r = 0; r < 16; ++r) pmax = fmaxf(pmax, p1[r]);
;   auto rr = __builtin_amdgcn_permlane32_swap(__float_as_uint(pmax), __float_as_uint(pmax), false, false);
;   return fmaxf(__uint_as_float(rr[0]), __uint_as_float(rr[1]));
; }
; __device__ __forceinline__ void decide(float pmax, float& m_reg, float& mn, float& alpha) {
;   const bool keep = __all(pmax - m_reg <= THRL);
;   mn = keep ? m_reg : fmaxf(m_reg, pmax); alpha = keep ? 1.f : __builtin_amdgcn_exp2f(m_reg - mn); m_reg = mn;
; }
; __device__ __forceinline__ void scoreConst(f32x16& p0, f32x16& p1, float& m_reg, float& alpha) {
;   const float pmax = rowmax32(p0, p1);
;   alpha = 1.f;
;   if (__builtin_expect(!__all(pmax <= THRL), 0)) { const float d = fmaxf(pmax, 0.f); m_reg += d; alpha = __builtin_amdgcn_exp2f(-d);
	s_add_i32 s60, s37, 0
	v_mfma_f32_32x32x16_bf16 v[64:79], v[96:99], v[148:151], v[64:79]
	ds_read_b64_tr_b16 v[148:149], v203 offset:0x200
	ds_read_b64_tr_b16 v[150:151], v203 offset:0xa00
	ds_read_b64_tr_b16 v[204:205], v203 offset:0x1200
	ds_read_b64_tr_b16 v[206:207], v203 offset:0x1a00
	ds_read_b64_tr_b16 v[208:209], v203 offset:0x2200
	ds_read_b64_tr_b16 v[210:211], v203 offset:0x2a00
	ds_read_b64_tr_b16 v[212:213], v203 offset:0x3200
	v_mfma_f32_32x32x16_bf16 v[64:79], v[100:103], v[152:155], v[64:79]
	ds_read_b64_tr_b16 v[214:215], v203 offset:0x3a00
	s_min_i32 s34, s34, s39
	s_waitcnt lgkmcnt(0)
	s_cmp_ge_i32 s34, s56
	s_cselect_b32 s35, s57, 0
	s_add_i32 s35, s35, s34
	s_lshl_b32 s34, s35, 6
	v_mfma_f32_32x32x16_bf16 v[64:79], v[104:107], v[156:159], v[64:79]
	v_mfma_f32_32x32x16_bf16 v[48:63], v[96:99], v[148:151], v[48:63]
	ds_read_b64_tr_b16 v[148:149], v203 offset:0x400
	ds_read_b64_tr_b16 v[150:151], v203 offset:0xc00
	ds_read_b64_tr_b16 v[152:153], v203 offset:0x1400
	ds_read_b64_tr_b16 v[154:155], v203 offset:0x1c00
	v_mfma_f32_32x32x16_bf16 v[64:79], v[108:111], v[160:163], v[64:79]
	ds_read_b64_tr_b16 v[160:161], v203 offset:0x2400
	ds_read_b64_tr_b16 v[162:163], v203 offset:0x2c00
	v_mfma_f32_32x32x16_bf16 v[48:63], v[100:103], v[204:207], v[48:63]
	ds_read_b64_tr_b16 v[204:205], v203 offset:0x3400
	ds_read_b64_tr_b16 v[206:207], v203 offset:0x3c00
	s_nop 0
	s_waitcnt lgkmcnt(0)
	ds_read_b64_tr_b16 v[216:217], v203 offset:0x600
	ds_read_b64_tr_b16 v[218:219], v203 offset:0xe00
	s_nop 0
	v_mfma_f32_32x32x16_bf16 v[32:47], v[96:99], v[148:151], v[32:47]
	s_lshl_b32 s98, s34, 12
	s_add_u32 s98, s30, s98
	s_addc_u32 s99, s31, 0
	v_mfma_f32_32x32x16_bf16 v[48:63], v[104:107], v[208:211], v[48:63]
	ds_read_b64_tr_b16 v[208:209], v203 offset:0x1600
	ds_read_b64_tr_b16 v[210:211], v203 offset:0x1e00
	ds_read_b64_tr_b16 v[220:221], v203 offset:0x2600
	ds_read_b64_tr_b16 v[222:223], v203 offset:0x2e00
	ds_read_b64_tr_b16 v[224:225], v203 offset:0x3600
	ds_read_b64_tr_b16 v[226:227], v203 offset:0x3e00
	v_mfma_f32_32x32x16_bf16 v[32:47], v[100:103], v[152:155], v[32:47]
	s_waitcnt vmcnt(0) lgkmcnt(0)
	global_load_dwordx4 v[156:159], v252, s[98:99] offset:2048
	s_nop 0
	global_load_dwordx4 v[148:151], v252, s[98:99]
	v_add_u32_e32 v203, s60, v183
	v_mfma_f32_32x32x16_bf16 v[32:47], v[104:107], v[160:163], v[32:47]
	global_load_dwordx4 v[160:163], v253, s[98:99] offset:2048
	s_nop 0
	global_load_dwordx4 v[152:155], v253, s[98:99]
	ds_write_b128 v203, v[6:9]
	v_add_u32_e32 v6, s60, v189
	ds_write_b128 v6, v[144:147]
	v_add_u32_e32 v6, s60, v190
	ds_write_b128 v6, v[2:5] offset:16384
	v_add_u32_e32 v2, s60, v191
	v_mfma_f32_32x32x16_bf16 v[16:31], v[96:99], v[216:219], v[16:31]
	ds_write_b128 v2, v[10:13] offset:16384
	v_max_f32_e32 v2, v128, v129
	v_max3_f32 v2, v2, v130, v131
	v_max3_f32 v2, v2, v132, v133
	v_max3_f32 v2, v2, v134, v135
	v_mfma_f32_32x32x16_bf16 v[16:31], v[100:103], v[208:211], v[16:31]
	v_max3_f32 v2, v2, v136, v137
	v_max3_f32 v2, v2, v138, v139
	v_max3_f32 v2, v2, v140, v141
	v_max3_f32 v2, v2, v142, v143
	v_max3_f32 v2, v2, v112, v113
	v_max3_f32 v2, v2, v114, v115
	v_max3_f32 v2, v2, v116, v117
	v_mfma_f32_32x32x16_bf16 v[16:31], v[104:107], v[220:223], v[16:31]
	v_max3_f32 v2, v2, v118, v119
	v_max3_f32 v2, v2, v120, v121
	v_max3_f32 v2, v2, v122, v123
	v_max3_f32 v2, v2, v124, v125
	v_max3_f32 v2, v2, v126, v127
	v_mov_b32_e32 v3, v2
	s_nop 1
	v_permlane32_swap_b32_e32 v2, v3
	v_mfma_f32_32x32x16_bf16 v[48:63], v[108:111], v[212:215], v[48:63]
	v_max_f32_e32 v2, v2, v3
	v_cmp_ge_f32_e32 vcc, s49, v2
	s_cmp_eq_u64 vcc, exec
	v_mov_b32_e32 v203, 1.0
	v_mfma_f32_32x32x16_bf16 v[32:47], v[108:111], v[204:207], v[32:47]
	v_mfma_f32_32x32x16_bf16 v[16:31], v[108:111], v[224:227], v[16:31]
	s_cbranch_scc1 .LBB0_220
	s_branch .LBB0_229

; __device__ __forceinline__ void finishSM(f32x16& p0, f32x16& p1, float alpha, float& l_reg, bf16x8& pa0, bf16x8& pa1, bf16x8& pa2, bf16x8& pa3) {
; #pragma unroll
;   for (int r = 0; r < 16; ++r) p1[r] = __builtin_amdgcn_exp2f(p1[r]);
;   float ps = 0;
; #pragma unroll
;   for (int r = 0; r < 16; ++r) ps += p0[r];
; #pragma unroll
;   for (int r = 0; r < 16; ++r) ps += p1[r];
;   { auto rr = __builtin_amdgcn_permlane32_swap(__float_as_uint(ps), __float_as_uint(ps), false, false);
;     ps = __uint_as_float(rr[0]) + __uint_as_float(rr[1]); }
;   l_reg = l_reg * alpha + ps;
;     ...
;   PK4(p0, 0, pa0); PK4(p0, 8, pa1); PK4(p1, 0, pa2); PK4(p1, 8, pa3);
;     ...
; }
; template <int NQ> __device__ __forceinline__ void qkt(f32x16& p0, f32x16& p1, const char* Ks, const bf16x8* qr, int r32, int hi, int kcolB) {
;   p0 = f32x16{}; p1 = f32x16{};
; #pragma unroll
;   for (int d0 = 0; d0 < NQ; ++d0) { const int cb = kcolB + (d0 * 16 + hi * 8) * 2;
;     bf16x8 b0 = *reinterpret_cast<const bf16x8*>(Ks + KSWZ(r32, cb));
;     bf16x8 b1 = *reinterpret_cast<const bf16x8*>(Ks + KSWZ(32 + r32, cb));
;     p0 = __builtin_amdgcn_mfma_f32_32x32x16_bf16(b0, qr[d0], p0, 0, 0, 0);
;     p1 = __builtin_amdgcn_mfma_f32_32x32x16_bf16(b1, qr[d0], p1, 0, 0, 0); }
; }
; __device__ __forceinline__ void qkt0(f32x16& p0, f32x16& p1, const char* Ks, const char* Qs, int r32, int hi, int kcolB, const f32x16& init) {
; #pragma unroll
;   for (int d0 = 0; d0 < 4; ++d0) { const int cb = kcolB + (d0 * 16 + hi * 8) * 2;
;     bf16x8 b0 = *reinterpret_cast<const bf16x8*>(Ks + KSWZ(r32, cb));
;     bf16x8 b1 = *reinterpret_cast<const bf16x8*>(Ks + KSWZ(32 + r32, cb));
;     bf16x8 qf = *reinterpret_cast<const bf16x8*>(Qs + r32 * 128 + (((2 * d0 + hi) ^ (r32 & 7)) << 4));
;     if (d0 == 0) { p0 = __builtin_amdgcn_mfma_f32_32x32x16_bf16(b0, qf, init, 0, 0, 0); p1 = __builtin_amdgcn_mfma_f32_32x32x16_bf16(b1, qf, init, 0, 0, 0); }
;     else { p0 = __builtin_amdgcn_mfma_f32_32x32x16_bf16(b0, qf, p0, 0, 0, 0); p1 = __builtin_amdgcn_mfma_f32_32x32x16_bf16(b1, qf, p1, 0, 0, 0); } }
; }
.LBB0_222:
	v_exp_f32_e32 v224, v128
	v_exp_f32_e32 v225, v129
	v_exp_f32_e32 v226, v130
	v_exp_f32_e32 v227, v131
	v_exp_f32_e32 v228, v132
	v_exp_f32_e32 v229, v133
	v_exp_f32_e32 v230, v134
	v_exp_f32_e32 v231, v135
	v_exp_f32_e32 v232, v136
	v_exp_f32_e32 v233, v137
	v_exp_f32_e32 v234, v138
	v_exp_f32_e32 v235, v139
	v_exp_f32_e32 v236, v140
	v_exp_f32_e32 v237, v141
	v_exp_f32_e32 v238, v142
	v_exp_f32_e32 v239, v143
	v_add_u32_e32 v2, s60, v193
	ds_read_b128 v[2:5], v2 offset:16384
	ds_read_b128 v[6:9], v181
	v_add_u32_e32 v96, s60, v194
	ds_read_b128 v[10:13], v180
	v_add_u32_e32 v97, s60, v195
	v_add_u32_e32 v208, s60, v199
	s_waitcnt lgkmcnt(1)
	v_mfma_f32_32x32x16_bf16 v[128:143], v[2:5], v[6:9], v[80:95]
	ds_read_b128 v[2:5], v96 offset:16384
	v_add_u32_e32 v96, s60, v197
	ds_read_b128 v[144:147], v96 offset:16384
	ds_read_b128 v[204:207], v97 offset:16384
	v_add_u32_e32 v209, s60, v196
	v_exp_f32_e32 v240, v114
	v_exp_f32_e32 v241, v115
	v_exp_f32_e32 v242, v116
	s_waitcnt lgkmcnt(0)
	v_mfma_f32_32x32x16_bf16 v[128:143], v[204:207], v[10:13], v[128:143]
	v_exp_f32_e32 v206, v112
	v_exp_f32_e32 v207, v113
	v_exp_f32_e32 v243, v117
	v_exp_f32_e32 v244, v118
	v_add_u32_e32 v216, s60, v200
	v_add_u32_e32 v220, s60, v198
	v_mfma_f32_32x32x16_bf16 v[96:111], v[2:5], v[6:9], v[80:95]
	ds_read_b128 v[2:5], v208 offset:16384
	ds_read_b128 v[6:9], v209 offset:16384
	ds_read_b128 v[208:211], v179
	ds_read_b128 v[212:215], v178
	ds_read_b128 v[216:219], v216 offset:16384
	ds_read_b128 v[220:223], v220 offset:16384
	v_cvt_pk_bf16_f32 v116, v224, v225
	v_cvt_pk_bf16_f32 v117, v226, v227
	v_cvt_pk_bf16_f32 v118, v228, v229
	s_nop 0
	v_permlane32_swap_b32_e32 v116, v118
	v_mfma_f32_32x32x16_bf16 v[96:111], v[144:147], v[10:13], v[96:111]
	v_exp_f32_e32 v10, v119
	v_exp_f32_e32 v11, v120
	v_exp_f32_e32 v12, v121
	v_exp_f32_e32 v13, v122
	v_exp_f32_e32 v144, v123
	v_exp_f32_e32 v145, v124
	v_exp_f32_e32 v146, v125
	s_waitcnt lgkmcnt(3)
	v_mfma_f32_32x32x16_bf16 v[128:143], v[6:9], v[208:211], v[128:143]
	v_add_f32_e32 v8, 0, v224
	v_add_f32_e32 v8, v225, v8
	v_add_f32_e32 v8, v226, v8
	v_add_f32_e32 v8, v227, v8
	v_add_f32_e32 v8, v228, v8
	v_exp_f32_e32 v6, v126
	v_exp_f32_e32 v7, v127
	v_mfma_f32_32x32x16_bf16 v[96:111], v[2:5], v[208:211], v[96:111]
	v_add_f32_e32 v2, v229, v8
	v_add_f32_e32 v2, v230, v2
	v_add_f32_e32 v2, v231, v2
	v_add_f32_e32 v2, v232, v2
	v_add_f32_e32 v2, v233, v2
	v_add_f32_e32 v2, v234, v2
	v_add_f32_e32 v2, v235, v2
	v_add_f32_e32 v2, v236, v2
	v_add_f32_e32 v2, v237, v2
	v_add_f32_e32 v2, v238, v2
	v_add_f32_e32 v2, v239, v2
	v_add_f32_e32 v2, v206, v2
	v_add_f32_e32 v2, v207, v2
	v_add_f32_e32 v2, v240, v2
	v_add_f32_e32 v2, v241, v2
	v_add_f32_e32 v2, v242, v2
	v_add_f32_e32 v2, v243, v2
	v_add_f32_e32 v2, v244, v2
	v_add_f32_e32 v2, v10, v2
	v_add_f32_e32 v2, v11, v2
	v_add_f32_e32 v2, v12, v2
	s_waitcnt lgkmcnt(0)
	v_mfma_f32_32x32x16_bf16 v[128:143], v[220:223], v[212:215], v[128:143]
	v_add_f32_e32 v2, v13, v2
	v_add_f32_e32 v2, v144, v2
	v_add_f32_e32 v2, v145, v2
	v_add_f32_e32 v2, v146, v2
	v_add_f32_e32 v2, v6, v2
	v_add_f32_e32 v204, v7, v2
	v_mov_b32_e32 v205, v204
	v_mfma_f32_32x32x16_bf16 v[96:111], v[216:219], v[212:215], v[96:111]
	v_cvt_pk_bf16_f32 v119, v230, v231
	v_cvt_pk_bf16_f32 v112, v232, v233
	v_cvt_pk_bf16_f32 v113, v234, v235
	v_cvt_pk_bf16_f32 v114, v236, v237
	v_cvt_pk_bf16_f32 v115, v238, v239
	v_permlane32_swap_b32_e32 v204, v205
	v_permlane32_swap_b32_e32 v112, v114
	v_permlane32_swap_b32_e32 v113, v115
	v_cvt_pk_bf16_f32 v120, v206, v207
	v_cvt_pk_bf16_f32 v121, v240, v241
	v_cvt_pk_bf16_f32 v122, v242, v243
	v_cvt_pk_bf16_f32 v123, v244, v10
	v_cvt_pk_bf16_f32 v124, v11, v12
	v_cvt_pk_bf16_f32 v125, v13, v144
	v_cvt_pk_bf16_f32 v126, v145, v146
	v_cvt_pk_bf16_f32 v127, v6, v7
	v_permlane32_swap_b32_e32 v117, v119
	v_permlane32_swap_b32_e32 v120, v122
	v_permlane32_swap_b32_e32 v121, v123
	v_permlane32_swap_b32_e32 v124, v126
	v_permlane32_swap_b32_e32 v125, v127
	v_add_u32_e32 v230, s59, v175
	ds_read_b64_tr_b16 v[2:3], v230 offset:0
	ds_read_b64_tr_b16 v[4:5], v230 offset:0x800
	ds_read_b64_tr_b16 v[6:7], v230 offset:0x1000
	ds_read_b64_tr_b16 v[8:9], v230 offset:0x1800
	ds_read_b64_tr_b16 v[10:11], v230 offset:0x2000
	ds_read_b64_tr_b16 v[12:13], v230 offset:0x2800
	ds_read_b64_tr_b16 v[144:145], v230 offset:0x3000
	ds_read_b64_tr_b16 v[146:147], v230 offset:0x3800
	s_add_i32 s58, s58, 2
	s_waitcnt lgkmcnt(0)
; __device__ __forceinline__ float rowmax32(const f32x16& p0, const f32x16& p1) {
;   float pmax = p0[0];
; #pragma unroll
;   for (int r = 1; r < 16; ++r) pmax = fmaxf(pmax, p0[r]);
; #pragma unroll
;   for (int r = 0; r < 16; ++r) pmax = fmaxf(pmax, p1[r]);
;   auto rr = __builtin_amdgcn_permlane32_swap(__float_as_uint(pmax), __float_as_uint(pmax), false, false);
;   return fmaxf(__uint_as_float(rr[0]), __uint_as_float(rr[1]));
; }
; __device__ __forceinline__ void decide(float pmax, float& m_reg, float& mn, float& alpha) {
;   const bool keep = __all(pmax - m_reg <= THRL);
;   mn = keep ? m_reg : fmaxf(m_reg, pmax); alpha = keep ? 1.f : __builtin_amdgcn_exp2f(m_reg - mn); m_reg = mn;
; }
; __device__ __forceinline__ void scoreConst(f32x16& p0, f32x16& p1, float& m_reg, float& alpha) {
;   const float pmax = rowmax32(p0, p1);
;   alpha = 1.f;
;   if (__builtin_expect(!__all(pmax <= THRL), 0)) { const float d = fmaxf(pmax, 0.f); m_reg += d; alpha = __builtin_amdgcn_exp2f(-d);
	s_add_i32 s34, s36, 0
	v_mfma_f32_32x32x16_bf16 v[64:79], v[116:119], v[2:5], v[64:79]
	ds_read_b64_tr_b16 v[2:3], v230 offset:0x200
	ds_read_b64_tr_b16 v[4:5], v230 offset:0xa00
	ds_read_b64_tr_b16 v[206:207], v230 offset:0x1200
	ds_read_b64_tr_b16 v[208:209], v230 offset:0x1a00
	ds_read_b64_tr_b16 v[210:211], v230 offset:0x2200
	ds_read_b64_tr_b16 v[212:213], v230 offset:0x2a00
	ds_read_b64_tr_b16 v[214:215], v230 offset:0x3200
	v_mfma_f32_32x32x16_bf16 v[64:79], v[112:115], v[6:9], v[64:79]
	ds_read_b64_tr_b16 v[216:217], v230 offset:0x3a00
	s_min_i32 s35, s58, s39
	s_waitcnt lgkmcnt(0)
	s_cmp_ge_i32 s35, s56
	s_cselect_b32 s60, s57, 0
	s_add_i32 s60, s60, s35
	s_lshl_b32 s35, s60, 6
	v_mfma_f32_32x32x16_bf16 v[48:63], v[116:119], v[2:5], v[48:63]
	ds_read_b64_tr_b16 v[2:3], v230 offset:0x400
	ds_read_b64_tr_b16 v[4:5], v230 offset:0xc00
	ds_read_b64_tr_b16 v[6:7], v230 offset:0x1400
	ds_read_b64_tr_b16 v[8:9], v230 offset:0x1c00
	v_mfma_f32_32x32x16_bf16 v[64:79], v[120:123], v[10:13], v[64:79]
	ds_read_b64_tr_b16 v[10:11], v230 offset:0x2400
	ds_read_b64_tr_b16 v[12:13], v230 offset:0x2c00
	v_mfma_f32_32x32x16_bf16 v[48:63], v[112:115], v[206:209], v[48:63]
	ds_read_b64_tr_b16 v[206:207], v230 offset:0x3400
	ds_read_b64_tr_b16 v[208:209], v230 offset:0x3c00
	s_nop 0
	s_waitcnt lgkmcnt(0)
	ds_read_b64_tr_b16 v[218:219], v230 offset:0x600
	ds_read_b64_tr_b16 v[220:221], v230 offset:0xe00
	s_nop 0
	v_mfma_f32_32x32x16_bf16 v[32:47], v[116:119], v[2:5], v[32:47]
	s_lshl_b32 s98, s35, 12
	s_add_u32 s98, s30, s98
	s_addc_u32 s99, s31, 0
	v_mfma_f32_32x32x16_bf16 v[48:63], v[120:123], v[210:213], v[48:63]
	ds_read_b64_tr_b16 v[210:211], v230 offset:0x1600
	ds_read_b64_tr_b16 v[212:213], v230 offset:0x1e00
	ds_read_b64_tr_b16 v[222:223], v230 offset:0x2600
	ds_read_b64_tr_b16 v[224:225], v230 offset:0x2e00
	ds_read_b64_tr_b16 v[226:227], v230 offset:0x3600
	ds_read_b64_tr_b16 v[228:229], v230 offset:0x3e00
	v_mfma_f32_32x32x16_bf16 v[32:47], v[112:115], v[6:9], v[32:47]
	s_waitcnt vmcnt(0) lgkmcnt(0)
	v_mfma_f32_32x32x16_bf16 v[48:63], v[124:127], v[214:217], v[48:63]
	global_load_dwordx4 v[6:9], v252, s[98:99] offset:2048
	s_nop 0
	global_load_dwordx4 v[2:5], v252, s[98:99]
	v_mfma_f32_32x32x16_bf16 v[64:79], v[124:127], v[144:147], v[64:79]
	v_mfma_f32_32x32x16_bf16 v[32:47], v[120:123], v[10:13], v[32:47]
	global_load_dwordx4 v[144:147], v253, s[98:99] offset:2048
	global_load_dwordx4 v[10:13], v253, s[98:99]
	v_add_u32_e32 v214, s34, v183
	ds_write_b128 v214, v[156:159]
	v_add_u32_e32 v156, s34, v189
	ds_write_b128 v156, v[160:163]
	v_add_u32_e32 v156, s34, v190
	ds_write_b128 v156, v[148:151] offset:16384
	v_mfma_f32_32x32x16_bf16 v[16:31], v[116:119], v[218:221], v[16:31]
	v_add_u32_e32 v148, s34, v191
	ds_write_b128 v148, v[152:155] offset:16384
	v_max_f32_e32 v148, v128, v129
	v_max3_f32 v148, v148, v130, v131
	v_max3_f32 v148, v148, v132, v133
	v_mfma_f32_32x32x16_bf16 v[16:31], v[112:115], v[210:213], v[16:31]
	v_max3_f32 v116, v148, v134, v135
	v_max3_f32 v116, v116, v136, v137
	v_max3_f32 v116, v116, v138, v139
	v_max3_f32 v116, v116, v140, v141
	v_max3_f32 v116, v116, v142, v143
	v_max3_f32 v116, v116, v96, v97
	v_max3_f32 v116, v116, v98, v99
	v_mfma_f32_32x32x16_bf16 v[16:31], v[120:123], v[222:225], v[16:31]
	v_max3_f32 v112, v116, v100, v101
	v_max3_f32 v112, v112, v102, v103
	v_max3_f32 v112, v112, v104, v105
	v_max3_f32 v112, v112, v106, v107
	v_max3_f32 v112, v112, v108, v109
	v_max3_f32 v112, v112, v110, v111
	v_mov_b32_e32 v113, v112
	v_mfma_f32_32x32x16_bf16 v[32:47], v[124:127], v[206:209], v[32:47]
	s_nop 0
	v_permlane32_swap_b32_e32 v112, v113
	v_max_f32_e32 v113, v112, v113
	v_cmp_ge_f32_e32 vcc, s49, v113
	s_cmp_eq_u64 vcc, exec
	v_mfma_f32_32x32x16_bf16 v[16:31], v[124:127], v[226:229], v[16:31]
	v_mov_b32_e32 v112, 1.0
	s_cbranch_scc1 .LBB0_227
	s_branch .LBB0_230
